# attention online softmax with deferred rescale (reference max advanced only when a row max rises by more than 8 log2 units)
# speedup vs baseline: 1.0509x; 1.0171x over previous
.LBB0_210:
	s_or_b64 exec, exec, s[10:11]
	v_max3_f32 v162, v64, s96, v65
	v_max3_f32 v162, v162, v66, v67
	v_max3_f32 v162, v162, v68, v69
	v_max3_f32 v162, v162, v70, v71
	v_max3_f32 v162, v162, v72, v73
	v_max3_f32 v162, v162, v74, v75
	v_max3_f32 v162, v162, v76, v77
	v_max3_f32 v162, v162, v78, v79
	v_max3_f32 v162, v162, v80, v81
	v_max3_f32 v162, v162, v82, v83
	v_max3_f32 v162, v162, v84, v85
	v_max3_f32 v162, v162, v86, v87
	v_max3_f32 v162, v162, v88, v89
	v_max3_f32 v162, v162, v90, v91
	v_max3_f32 v162, v162, v92, v93
	v_max3_f32 v162, v162, v94, v95
	v_mov_b32_e32 v163, v162
	s_nop 1
	v_permlane32_swap_b32_e32 v162, v163
	v_max_f32_e32 v162, v162, v163
	v_sub_f32_e32 v163, v162, v170
	v_cmp_lt_f32_e32 vcc, 0x41000000, v163
	s_cbranch_vccnz .Lda_upd0
	v_mov_b32_e32 v234, v170
	v_mov_b32_e32 v170, 1.0
	s_branch .LBB0_212
.Lda_upd0:
	v_max_f32_e32 v234, v170, v162
	v_sub_f32_e32 v162, v170, v234
	v_exp_f32_e32 v170, v162
	s_nop 0
	v_pk_mul_f32 v[62:63], v[62:63], v[170:171] op_sel_hi:[1,0]
	v_pk_mul_f32 v[60:61], v[60:61], v[170:171] op_sel_hi:[1,0]
	v_pk_mul_f32 v[58:59], v[58:59], v[170:171] op_sel_hi:[1,0]
	v_pk_mul_f32 v[56:57], v[56:57], v[170:171] op_sel_hi:[1,0]
	v_pk_mul_f32 v[54:55], v[54:55], v[170:171] op_sel_hi:[1,0]
	v_pk_mul_f32 v[52:53], v[52:53], v[170:171] op_sel_hi:[1,0]
	v_pk_mul_f32 v[50:51], v[50:51], v[170:171] op_sel_hi:[1,0]
	v_pk_mul_f32 v[48:49], v[48:49], v[170:171] op_sel_hi:[1,0]
	v_pk_mul_f32 v[46:47], v[46:47], v[170:171] op_sel_hi:[1,0]
	v_pk_mul_f32 v[44:45], v[44:45], v[170:171] op_sel_hi:[1,0]
	v_pk_mul_f32 v[42:43], v[42:43], v[170:171] op_sel_hi:[1,0]
	v_pk_mul_f32 v[40:41], v[40:41], v[170:171] op_sel_hi:[1,0]
	v_pk_mul_f32 v[38:39], v[38:39], v[170:171] op_sel_hi:[1,0]
	v_pk_mul_f32 v[36:37], v[36:37], v[170:171] op_sel_hi:[1,0]
	v_pk_mul_f32 v[34:35], v[34:35], v[170:171] op_sel_hi:[1,0]
	v_pk_mul_f32 v[32:33], v[32:33], v[170:171] op_sel_hi:[1,0]
	v_pk_mul_f32 v[30:31], v[30:31], v[170:171] op_sel_hi:[1,0]
	v_pk_mul_f32 v[28:29], v[28:29], v[170:171] op_sel_hi:[1,0]
	v_pk_mul_f32 v[26:27], v[26:27], v[170:171] op_sel_hi:[1,0]
	v_pk_mul_f32 v[24:25], v[24:25], v[170:171] op_sel_hi:[1,0]
	v_pk_mul_f32 v[22:23], v[22:23], v[170:171] op_sel_hi:[1,0]
	v_pk_mul_f32 v[20:21], v[20:21], v[170:171] op_sel_hi:[1,0]
	v_pk_mul_f32 v[18:19], v[18:19], v[170:171] op_sel_hi:[1,0]
	v_pk_mul_f32 v[16:17], v[16:17], v[170:171] op_sel_hi:[1,0]
	v_pk_mul_f32 v[14:15], v[14:15], v[170:171] op_sel_hi:[1,0]
	v_pk_mul_f32 v[12:13], v[12:13], v[170:171] op_sel_hi:[1,0]
	v_pk_mul_f32 v[10:11], v[10:11], v[170:171] op_sel_hi:[1,0]
	v_pk_mul_f32 v[8:9], v[8:9], v[170:171] op_sel_hi:[1,0]
	v_pk_mul_f32 v[6:7], v[6:7], v[170:171] op_sel_hi:[1,0]
	v_pk_mul_f32 v[4:5], v[4:5], v[170:171] op_sel_hi:[1,0]
	v_pk_mul_f32 v[2:3], v[2:3], v[170:171] op_sel_hi:[1,0]
	v_pk_mul_f32 v[0:1], v[0:1], v[170:171] op_sel_hi:[1,0]

.LBB0_218:
	s_or_b64 exec, exec, s[8:9]
	v_max3_f32 v162, v96, s96, v97
	v_max3_f32 v162, v162, v98, v99
	v_max3_f32 v162, v162, v100, v101
	v_max3_f32 v162, v162, v102, v103
	v_max3_f32 v162, v162, v104, v105
	v_max3_f32 v162, v162, v106, v107
	v_max3_f32 v162, v162, v108, v109
	v_max3_f32 v162, v162, v110, v111
	v_max3_f32 v162, v162, v112, v113
	v_max3_f32 v162, v162, v114, v115
	v_max3_f32 v162, v162, v116, v117
	v_max3_f32 v162, v162, v118, v119
	v_max3_f32 v162, v162, v120, v121
	v_max3_f32 v162, v162, v122, v123
	v_max3_f32 v162, v162, v124, v125
	v_max3_f32 v162, v162, v126, v127
	v_mov_b32_e32 v163, v162
	s_nop 1
	v_permlane32_swap_b32_e32 v162, v163
	v_max_f32_e32 v162, v162, v163
	v_sub_f32_e32 v163, v162, v170
	v_cmp_lt_f32_e32 vcc, 0x41000000, v163
	s_cbranch_vccnz .Lda_upd1
	v_mov_b32_e32 v234, v170
	v_mov_b32_e32 v170, 1.0
	s_branch .LBB0_203
.Lda_upd1:
	v_max_f32_e32 v234, v170, v162
	v_sub_f32_e32 v162, v170, v234
	v_exp_f32_e32 v170, v162
	s_nop 0
	v_pk_mul_f32 v[62:63], v[62:63], v[170:171] op_sel_hi:[1,0]
	v_pk_mul_f32 v[60:61], v[60:61], v[170:171] op_sel_hi:[1,0]
	v_pk_mul_f32 v[58:59], v[58:59], v[170:171] op_sel_hi:[1,0]
	v_pk_mul_f32 v[56:57], v[56:57], v[170:171] op_sel_hi:[1,0]
	v_pk_mul_f32 v[54:55], v[54:55], v[170:171] op_sel_hi:[1,0]
	v_pk_mul_f32 v[52:53], v[52:53], v[170:171] op_sel_hi:[1,0]
	v_pk_mul_f32 v[50:51], v[50:51], v[170:171] op_sel_hi:[1,0]
	v_pk_mul_f32 v[48:49], v[48:49], v[170:171] op_sel_hi:[1,0]
	v_pk_mul_f32 v[46:47], v[46:47], v[170:171] op_sel_hi:[1,0]
	v_pk_mul_f32 v[44:45], v[44:45], v[170:171] op_sel_hi:[1,0]
	v_pk_mul_f32 v[42:43], v[42:43], v[170:171] op_sel_hi:[1,0]
	v_pk_mul_f32 v[40:41], v[40:41], v[170:171] op_sel_hi:[1,0]
	v_pk_mul_f32 v[38:39], v[38:39], v[170:171] op_sel_hi:[1,0]
	v_pk_mul_f32 v[36:37], v[36:37], v[170:171] op_sel_hi:[1,0]
	v_pk_mul_f32 v[34:35], v[34:35], v[170:171] op_sel_hi:[1,0]
	v_pk_mul_f32 v[32:33], v[32:33], v[170:171] op_sel_hi:[1,0]
	v_pk_mul_f32 v[30:31], v[30:31], v[170:171] op_sel_hi:[1,0]
	v_pk_mul_f32 v[28:29], v[28:29], v[170:171] op_sel_hi:[1,0]
	v_pk_mul_f32 v[26:27], v[26:27], v[170:171] op_sel_hi:[1,0]
	v_pk_mul_f32 v[24:25], v[24:25], v[170:171] op_sel_hi:[1,0]
	v_pk_mul_f32 v[22:23], v[22:23], v[170:171] op_sel_hi:[1,0]
	v_pk_mul_f32 v[20:21], v[20:21], v[170:171] op_sel_hi:[1,0]
	v_pk_mul_f32 v[18:19], v[18:19], v[170:171] op_sel_hi:[1,0]
	v_pk_mul_f32 v[16:17], v[16:17], v[170:171] op_sel_hi:[1,0]
	v_pk_mul_f32 v[14:15], v[14:15], v[170:171] op_sel_hi:[1,0]
	v_pk_mul_f32 v[12:13], v[12:13], v[170:171] op_sel_hi:[1,0]
	v_pk_mul_f32 v[10:11], v[10:11], v[170:171] op_sel_hi:[1,0]
	v_pk_mul_f32 v[8:9], v[8:9], v[170:171] op_sel_hi:[1,0]
	v_pk_mul_f32 v[6:7], v[6:7], v[170:171] op_sel_hi:[1,0]
	v_pk_mul_f32 v[4:5], v[4:5], v[170:171] op_sel_hi:[1,0]
	v_pk_mul_f32 v[2:3], v[2:3], v[170:171] op_sel_hi:[1,0]
	v_pk_mul_f32 v[0:1], v[0:1], v[170:171] op_sel_hi:[1,0]
	s_branch .LBB0_203
